# GEMM phase prologues: both K-tiles' staging loads issued up front by both halves, stagger barrier and first wait moved below them
# speedup vs baseline: 1.0080x; 1.0078x over previous
; #define PG8_STAGE(bufoff, gbase, voff) do { _Pragma("unroll") for (int _i = 0; _i < 2; ++_i) \
;         __builtin_amdgcn_global_load_lds((const unsigned*)((const char*)(gbase) + (voff)[_i]), (PG8_LAS unsigned*)(lds + (bufoff) + ldsw + _i * 8192), 16, 0, 0); } while (0)
; #define PG8_WAIT_V(n) asm volatile("s_waitcnt vmcnt(" #n ")" ::: "memory")
; #define PG8_BAR __builtin_amdgcn_s_barrier()
; template <class Epi, class Sched, bool ALIGN_EPI = false, bool SP2 = false>
; __device__ __forceinline__ void gemm_phase(PG8_LAS unsigned char* lds, const Gemm g, const Sched& S, const Epi& E) {
;     ...
;     if constexpr (SP2) {
;         PG8_STAGE(PG8_SB(0, 0), cB, voffB); PG8_STAGE(PG8_SB(0, 1), cB + hstep, voffB); PG8_STAGE(PG8_SA(0, 0), cA, voffA); PG8_STAGE(PG8_SA(0, 1), cA + hstep, voffA);
;         if (wr == 1) PG8_BAR;
;         PG8_WAIT_V(2); PG8_BAR;
;         PG8_STAGE(PG8_SB(1, 0), cB + kstep, voffB); PG8_STAGE(PG8_SA(1, 0), cA + kstep, voffA); PG8_STAGE(PG8_SB(1, 1), cB + hstep + kstep, voffB);
;         PG8_WAIT_V(6); PG8_BAR;
.LBB0_61:
	s_lshl_b32 s7, s7, 5
	s_mov_b64 s[48:49], 0x80
	s_and_b32 s7, s7, 0x60
	s_add_i32 m0, s1, 0x18000
	v_lshl_add_u64 v[6:7], v[6:7], 0, s[48:49]
	s_lshl_b32 s5, s6, 13
	s_lshl_b32 s60, s7, 7
	global_load_lds_dwordx4 v[6:7], off
	v_lshl_add_u64 v[4:5], v[4:5], 0, s[48:49]
	s_add_i32 m0, s1, 0x1a000
	s_add_i32 s80, s1, 0x8000
	s_add_i32 s81, s1, 0xa000
	global_load_lds_dwordx4 v[4:5], off
	v_lshl_add_u64 v[0:1], v[0:1], 0, s[48:49]
	s_mov_b32 m0, s80
	s_add_u32 s24, s76, 0x80080
	global_load_lds_dwordx4 v[0:1], off
	v_lshl_add_u64 v[0:1], v[2:3], 0, s[48:49]
	s_mov_b32 m0, s81
	s_addc_u32 s25, s77, 0
	global_load_lds_dwordx4 v[0:1], off
	s_add_i32 m0, s1, 0x1c000
	v_lshl_add_u64 v[0:1], s[24:25], 0, v[134:135]
	global_load_lds_dwordx4 v[0:1], off
	v_lshl_add_u64 v[0:1], s[24:25], 0, v[138:139]
	s_add_i32 m0, s1, 0x1e000
	s_cmpk_lt_u32 s14, 0x100
	global_load_lds_dwordx4 v[0:1], off
	s_cmp_lg_u32 s6, 1
	s_cbranch_scc1 .Lgp_skip_0
	s_barrier
.Lgp_skip_0:
	s_cmpk_lt_u32 s14, 0x100
	s_waitcnt vmcnt(8)
	s_barrier
	v_lshrrev_b32_e32 v1, 1, v8
	v_and_b32_e32 v1, 24, v1
	v_and_b32_e32 v0, 15, v8
	v_lshlrev_b32_e32 v2, 1, v1
	v_lshl_or_b32 v143, s6, 6, v0
	v_lshl_or_b32 v0, v0, 6, v2
	v_lshlrev_b32_e32 v2, 2, v8
	v_and_b32_e32 v2, 32, v2
	v_bitop3_b32 v3, v0, s5, v2 bitop3:0xde
	v_bitop3_b32 v158, v0, s60, v2 bitop3:0xde
	v_lshlrev_b32_e32 v0, 15, v9
	v_and_b32_e32 v0, 0xffff0000, v0
	v_or_b32_e32 v142, s7, v1
	v_lshl_add_u32 v0, v10, 12, v0
	v_and_b32_e32 v1, 1, v9
	v_lshl_or_b32 v0, v1, 6, v0
	v_lshl_add_u32 v144, v11, 1, v0
	v_lshlrev_b32_e32 v0, 15, v12
	v_and_b32_e32 v0, 0xffff0000, v0
	s_waitcnt vmcnt(6)
	v_lshl_add_u32 v0, v13, 12, v0
	v_and_b32_e32 v1, 1, v12
	s_cselect_b64 s[60:61], -1, 0
	v_lshl_or_b32 v0, v1, 6, v0
	s_add_i32 s85, 0, 0x10000
	s_add_i32 s86, 0, 0x14000
	s_movk_i32 s64, 0xf800
	s_ashr_i32 s82, s56, 31
	s_mov_b32 s83, s56
	s_ashr_i32 s84, s2, 31
	v_mov_b32_e32 v145, v141
	v_lshl_add_u32 v146, v14, 1, v0
	v_mov_b32_e32 v147, v141
	v_mov_b64_e32 v[148:149], 0x600
	v_mov_b64_e32 v[150:151], 0x5ff
	s_mov_b64 s[62:63], 0x100
	v_add_u32_e32 v159, s85, v158
	v_add_u32_e32 v160, s86, v158
	v_add_u32_e32 v161, 0, v3
	s_mov_b32 s65, -1
	s_mov_b32 s87, 0
	s_barrier
	s_branch .LBB0_64

; #define PG8_STAGE(bufoff, gbase, voff) do { _Pragma("unroll") for (int _i = 0; _i < 2; ++_i) \
;         __builtin_amdgcn_global_load_lds((const unsigned*)((const char*)(gbase) + (voff)[_i]), (PG8_LAS unsigned*)(lds + (bufoff) + ldsw + _i * 8192), 16, 0, 0); } while (0)
; #define PG8_WAIT_V(n) asm volatile("s_waitcnt vmcnt(" #n ")" ::: "memory")
; #define PG8_BAR __builtin_amdgcn_s_barrier()
; template <class Epi, class Sched, bool ALIGN_EPI = false, bool SP2 = false>
; __device__ __forceinline__ void gemm_phase(PG8_LAS unsigned char* lds, const Gemm g, const Sched& S, const Epi& E) {
;     ...
;     if constexpr (SP2) {
;         PG8_STAGE(PG8_SB(0, 0), cB, voffB); PG8_STAGE(PG8_SB(0, 1), cB + hstep, voffB); PG8_STAGE(PG8_SA(0, 0), cA, voffA); PG8_STAGE(PG8_SA(0, 1), cA + hstep, voffA);
;         if (wr == 1) PG8_BAR;
;         PG8_WAIT_V(2); PG8_BAR;
;         PG8_STAGE(PG8_SB(1, 0), cB + kstep, voffB); PG8_STAGE(PG8_SA(1, 0), cA + kstep, voffA); PG8_STAGE(PG8_SB(1, 1), cB + hstep + kstep, voffB);
;         PG8_WAIT_V(6); PG8_BAR;
.LBB0_235:
	s_lshl_b32 s10, s10, 5
	s_and_b32 s44, s10, 0x60
	s_mov_b64 s[10:11], 0x80
	s_add_i32 m0, s33, 0x18000
	v_lshl_add_u64 v[6:7], v[6:7], 0, s[10:11]
	s_lshl_b32 s15, s5, 13
	s_lshl_b32 s45, s44, 7
	global_load_lds_dwordx4 v[6:7], off
	v_lshl_add_u64 v[4:5], v[4:5], 0, s[10:11]
	s_add_i32 m0, s33, 0x1a000
	s_add_i32 s78, s33, 0x8000
	s_add_i32 s79, s33, 0xa000
	global_load_lds_dwordx4 v[4:5], off
	v_lshl_add_u64 v[0:1], v[0:1], 0, s[10:11]
	s_mov_b32 m0, s78
	s_add_u32 s24, s72, 0x80080
	global_load_lds_dwordx4 v[0:1], off
	v_lshl_add_u64 v[0:1], v[2:3], 0, s[10:11]
	s_mov_b32 m0, s79
	s_addc_u32 s25, s73, 0
	global_load_lds_dwordx4 v[0:1], off
	s_add_i32 m0, s33, 0x1c000
	v_lshl_add_u64 v[0:1], s[24:25], 0, v[130:131]
	global_load_lds_dwordx4 v[0:1], off
	v_lshl_add_u64 v[0:1], s[24:25], 0, v[134:135]
	s_add_i32 m0, s33, 0x1e000
	s_cmpk_lt_u32 s14, 0x100
	global_load_lds_dwordx4 v[0:1], off
	s_cmp_lg_u32 s5, 1
	s_cbranch_scc1 .Lgp_skip_1
	s_barrier
.Lgp_skip_1:
	s_cmpk_lt_u32 s14, 0x100
	s_waitcnt vmcnt(8)
	s_barrier
	v_lshrrev_b32_e32 v1, 1, v8
	v_and_b32_e32 v1, 24, v1
	v_and_b32_e32 v0, 15, v8
	v_lshlrev_b32_e32 v2, 1, v1
	v_lshl_or_b32 v150, s5, 6, v0
	v_lshl_or_b32 v0, v0, 6, v2
	v_lshlrev_b32_e32 v2, 2, v8
	v_and_b32_e32 v2, 32, v2
	v_bitop3_b32 v3, v0, s15, v2 bitop3:0xde
	v_bitop3_b32 v151, v0, s45, v2 bitop3:0xde
	v_lshlrev_b32_e32 v0, 15, v9
	v_and_b32_e32 v0, 0xffff0000, v0
	v_or_b32_e32 v152, s44, v1
	v_lshl_add_u32 v0, v10, 12, v0
	v_and_b32_e32 v1, 1, v9
	v_lshl_or_b32 v0, v1, 6, v0
	v_lshl_add_u32 v136, v11, 1, v0
	v_lshlrev_b32_e32 v0, 15, v12
	v_and_b32_e32 v0, 0xffff0000, v0
	s_waitcnt vmcnt(6)
	v_lshl_add_u32 v0, v13, 12, v0
	v_and_b32_e32 v1, 1, v12
	s_cselect_b64 s[14:15], -1, 0
	v_lshl_or_b32 v0, v1, 6, v0
	s_add_i32 s82, 0, 0x10000
	s_add_i32 s83, 0, 0x14000
	s_sext_i32_i8 s24, s4
	s_ashr_i32 s80, s56, 31
	s_mov_b32 s81, s56
	v_mov_b32_e32 v137, v131
	v_lshl_add_u32 v138, v14, 1, v0
	v_mov_b32_e32 v139, v131
	v_mov_b64_e32 v[140:141], 0x200
	v_mov_b64_e32 v[142:143], 0x1ff
	v_add_u32_e32 v153, s82, v151
	v_add_u32_e32 v154, s83, v151
	v_add_u32_e32 v155, 0, v3
	s_mov_b64 s[44:45], 0x50000
	s_mov_b64 s[48:49], 0x58000
	s_barrier
	s_branch .LBB0_238

; #define PG8_STAGE(bufoff, gbase, voff) do { _Pragma("unroll") for (int _i = 0; _i < 2; ++_i) \
;         __builtin_amdgcn_global_load_lds((const unsigned*)((const char*)(gbase) + (voff)[_i]), (PG8_LAS unsigned*)(lds + (bufoff) + ldsw + _i * 8192), 16, 0, 0); } while (0)
; #define PG8_WAIT_V(n) asm volatile("s_waitcnt vmcnt(" #n ")" ::: "memory")
; #define PG8_BAR __builtin_amdgcn_s_barrier()
; template <class Epi, class Sched, bool ALIGN_EPI = false, bool SP2 = false>
; __device__ __forceinline__ void gemm_phase(PG8_LAS unsigned char* lds, const Gemm g, const Sched& S, const Epi& E) {
;     ...
;     if constexpr (SP2) {
;         PG8_STAGE(PG8_SB(0, 0), cB, voffB); PG8_STAGE(PG8_SB(0, 1), cB + hstep, voffB); PG8_STAGE(PG8_SA(0, 0), cA, voffA); PG8_STAGE(PG8_SA(0, 1), cA + hstep, voffA);
;         if (wr == 1) PG8_BAR;
;         PG8_WAIT_V(2); PG8_BAR;
;         PG8_STAGE(PG8_SB(1, 0), cB + kstep, voffB); PG8_STAGE(PG8_SA(1, 0), cA + kstep, voffA); PG8_STAGE(PG8_SB(1, 1), cB + hstep + kstep, voffB);
;         PG8_WAIT_V(6); PG8_BAR;
.LBB0_366:
	s_lshl_b32 s10, s10, 5
	s_and_b32 s36, s10, 0x60
	s_mov_b64 s[10:11], 0x80
	s_add_i32 m0, s33, 0x18000
	v_lshl_add_u64 v[6:7], v[6:7], 0, s[10:11]
	s_lshl_b32 s15, s5, 13
	s_lshl_b32 s37, s36, 7
	global_load_lds_dwordx4 v[6:7], off
	v_lshl_add_u64 v[4:5], v[4:5], 0, s[10:11]
	s_add_i32 m0, s33, 0x1a000
	s_add_i32 s76, s33, 0x8000
	s_add_i32 s77, s33, 0xa000
	global_load_lds_dwordx4 v[4:5], off
	v_lshl_add_u64 v[0:1], v[0:1], 0, s[10:11]
	s_mov_b32 m0, s76
	s_add_u32 s24, s70, 0x80080
	global_load_lds_dwordx4 v[0:1], off
	v_lshl_add_u64 v[0:1], v[2:3], 0, s[10:11]
	s_mov_b32 m0, s77
	s_addc_u32 s25, s71, 0
	global_load_lds_dwordx4 v[0:1], off
	s_add_i32 m0, s33, 0x1c000
	v_lshl_add_u64 v[0:1], s[24:25], 0, v[130:131]
	global_load_lds_dwordx4 v[0:1], off
	v_lshl_add_u64 v[0:1], s[24:25], 0, v[134:135]
	s_add_i32 m0, s33, 0x1e000
	s_cmpk_lt_u32 s14, 0x100
	global_load_lds_dwordx4 v[0:1], off
	s_cmp_lg_u32 s5, 1
	s_cbranch_scc1 .Lgp_skip_2
	s_barrier
.Lgp_skip_2:
	s_cmpk_lt_u32 s14, 0x100
	s_waitcnt vmcnt(8)
	s_barrier
	v_lshrrev_b32_e32 v1, 1, v8
	v_and_b32_e32 v1, 24, v1
	v_and_b32_e32 v0, 15, v8
	v_lshlrev_b32_e32 v2, 1, v1
	v_lshl_or_b32 v146, s5, 6, v0
	v_lshl_or_b32 v0, v0, 6, v2
	v_lshlrev_b32_e32 v2, 2, v8
	v_and_b32_e32 v2, 32, v2
	v_bitop3_b32 v3, v0, s15, v2 bitop3:0xde
	v_bitop3_b32 v147, v0, s37, v2 bitop3:0xde
	v_lshlrev_b32_e32 v0, 15, v9
	v_and_b32_e32 v0, 0xffff0000, v0
	v_or_b32_e32 v148, s36, v1
	v_lshl_add_u32 v0, v10, 12, v0
	v_and_b32_e32 v1, 1, v9
	v_lshl_or_b32 v0, v1, 6, v0
	v_lshl_add_u32 v136, v11, 1, v0
	v_lshlrev_b32_e32 v0, 15, v12
	v_and_b32_e32 v0, 0xffff0000, v0
	s_waitcnt vmcnt(6)
	v_lshl_add_u32 v0, v13, 12, v0
	v_and_b32_e32 v1, 1, v12
	s_cselect_b64 s[14:15], -1, 0
	v_lshl_or_b32 v0, v1, 6, v0
	s_add_i32 s80, 0, 0x10000
	s_add_i32 s81, 0, 0x14000
	s_sext_i32_i8 s24, s4
	s_ashr_i32 s78, s56, 31
	s_mov_b32 s79, s56
	v_mov_b32_e32 v137, v131
	v_lshl_add_u32 v138, v14, 1, v0
	v_mov_b32_e32 v139, v131
	v_mov_b64_e32 v[140:141], 0x400
	v_mov_b64_e32 v[142:143], 0x3ff
	v_add_u32_e32 v149, s80, v147
	v_add_u32_e32 v150, s81, v147
	v_add_u32_e32 v151, 0, v3
	s_mov_b32 s82, 0x240000
	s_mov_b64 s[36:37], 0x280000
	s_mov_b32 s83, 0x280000
	s_mov_b64 s[44:45], 0x2c0000
	s_mov_b32 s84, 0x2c0000
	s_barrier
	s_branch .LBB0_369

; #define PG8_STAGE(bufoff, gbase, voff) do { _Pragma("unroll") for (int _i = 0; _i < 2; ++_i) \
;         __builtin_amdgcn_global_load_lds((const unsigned*)((const char*)(gbase) + (voff)[_i]), (PG8_LAS unsigned*)(lds + (bufoff) + ldsw + _i * 8192), 16, 0, 0); } while (0)
; #define PG8_WAIT_V(n) asm volatile("s_waitcnt vmcnt(" #n ")" ::: "memory")
; #define PG8_BAR __builtin_amdgcn_s_barrier()
; template <class Epi, class Sched, bool ALIGN_EPI = false, bool SP2 = false>
; __device__ __forceinline__ void gemm_phase(PG8_LAS unsigned char* lds, const Gemm g, const Sched& S, const Epi& E) {
;     ...
;     if constexpr (SP2) {
;         PG8_STAGE(PG8_SB(0, 0), cB, voffB); PG8_STAGE(PG8_SB(0, 1), cB + hstep, voffB); PG8_STAGE(PG8_SA(0, 0), cA, voffA); PG8_STAGE(PG8_SA(0, 1), cA + hstep, voffA);
;         if (wr == 1) PG8_BAR;
;         PG8_WAIT_V(2); PG8_BAR;
;         PG8_STAGE(PG8_SB(1, 0), cB + kstep, voffB); PG8_STAGE(PG8_SA(1, 0), cA + kstep, voffA); PG8_STAGE(PG8_SB(1, 1), cB + hstep + kstep, voffB);
;         PG8_WAIT_V(6); PG8_BAR;
.LBB0_442:
	s_lshl_b32 s5, s5, 5
	s_mov_b64 s[14:15], 0x80
	s_and_b32 s5, s5, 0x60
	s_add_i32 m0, s33, 0x18000
	v_lshl_add_u64 v[6:7], v[6:7], 0, s[14:15]
	s_lshl_b32 s37, s36, 13
	s_lshl_b32 s48, s5, 7
	global_load_lds_dwordx4 v[6:7], off
	v_lshl_add_u64 v[4:5], v[4:5], 0, s[14:15]
	s_add_i32 m0, s33, 0x1a000
	s_add_i32 s78, s33, 0x8000
	s_add_i32 s79, s33, 0xa000
	global_load_lds_dwordx4 v[4:5], off
	v_lshl_add_u64 v[0:1], v[0:1], 0, s[14:15]
	s_mov_b32 m0, s78
	s_add_u32 s44, s72, 0x200080
	global_load_lds_dwordx4 v[0:1], off
	v_lshl_add_u64 v[0:1], v[2:3], 0, s[14:15]
	s_mov_b32 m0, s79
	s_addc_u32 s45, s73, 0
	global_load_lds_dwordx4 v[0:1], off
	s_add_i32 m0, s33, 0x1c000
	v_lshl_add_u64 v[0:1], s[44:45], 0, v[170:171]
	global_load_lds_dwordx4 v[0:1], off
	v_lshl_add_u64 v[0:1], s[44:45], 0, v[174:175]
	s_add_i32 m0, s33, 0x1e000
	s_cmpk_lt_u32 s25, 0x100
	global_load_lds_dwordx4 v[0:1], off
	s_cmp_lg_u32 s36, 1
	s_cbranch_scc1 .Lgp_skip_3
	s_barrier
.Lgp_skip_3:
	s_cmpk_lt_u32 s25, 0x100
	s_waitcnt vmcnt(8)
	s_barrier
	v_lshrrev_b32_e32 v1, 1, v8
	v_and_b32_e32 v1, 24, v1
	v_and_b32_e32 v0, 15, v8
	v_lshlrev_b32_e32 v2, 1, v1
	v_lshl_or_b32 v199, s36, 6, v0
	v_lshl_or_b32 v0, v0, 6, v2
	v_lshlrev_b32_e32 v2, 2, v8
	v_and_b32_e32 v2, 32, v2
	v_bitop3_b32 v3, v0, s37, v2 bitop3:0xde
	v_bitop3_b32 v200, v0, s48, v2 bitop3:0xde
	v_lshlrev_b32_e32 v0, 17, v9
	v_and_b32_e32 v0, 0xfffc0000, v0
	v_or_b32_e32 v201, s5, v1
	v_lshl_add_u32 v0, v10, 14, v0
	v_and_b32_e32 v1, 1, v9
	v_lshl_or_b32 v0, v1, 6, v0
	v_lshl_add_u32 v176, v11, 1, v0
	v_lshlrev_b32_e32 v0, 17, v12
	v_and_b32_e32 v0, 0xfffc0000, v0
	s_waitcnt vmcnt(6)
	v_lshl_add_u32 v0, v13, 14, v0
	v_and_b32_e32 v1, 1, v12
	s_cselect_b64 s[36:37], -1, 0
	v_lshl_or_b32 v0, v1, 6, v0
	s_add_i32 s82, 0, 0x10000
	s_add_i32 s83, 0, 0x14000
	s_sext_i32_i8 s24, s4
	s_ashr_i32 s80, s56, 31
	s_mov_b32 s81, s56
	v_mov_b32_e32 v177, v171
	v_lshl_add_u32 v178, v14, 1, v0
	v_mov_b32_e32 v179, v171
	v_mov_b64_e32 v[180:181], 0x100
	v_mov_b64_e32 v[182:183], 0xff
	v_add_u32_e32 v202, s82, v200
	v_add_u32_e32 v203, s83, v200
	v_add_u32_e32 v204, 0, v3
	s_mov_b64 s[44:45], 0xa0000
	s_mov_b64 s[48:49], 0xb0000
	s_barrier
	s_branch .LBB0_445

; #define PG8_STAGE(bufoff, gbase, voff) do { _Pragma("unroll") for (int _i = 0; _i < 2; ++_i) \
;         __builtin_amdgcn_global_load_lds((const unsigned*)((const char*)(gbase) + (voff)[_i]), (PG8_LAS unsigned*)(lds + (bufoff) + ldsw + _i * 8192), 16, 0, 0); } while (0)
; #define PG8_WAIT_V(n) asm volatile("s_waitcnt vmcnt(" #n ")" ::: "memory")
; #define PG8_BAR __builtin_amdgcn_s_barrier()
; template <class Epi, class Sched, bool ALIGN_EPI = false, bool SP2 = false>
; __device__ __forceinline__ void gemm_phase(PG8_LAS unsigned char* lds, const Gemm g, const Sched& S, const Epi& E) {
;     ...
;     if constexpr (SP2) {
;         PG8_STAGE(PG8_SB(0, 0), cB, voffB); PG8_STAGE(PG8_SB(0, 1), cB + hstep, voffB); PG8_STAGE(PG8_SA(0, 0), cA, voffA); PG8_STAGE(PG8_SA(0, 1), cA + hstep, voffA);
;         if (wr == 1) PG8_BAR;
;         PG8_WAIT_V(2); PG8_BAR;
;         PG8_STAGE(PG8_SB(1, 0), cB + kstep, voffB); PG8_STAGE(PG8_SA(1, 0), cA + kstep, voffA); PG8_STAGE(PG8_SB(1, 1), cB + hstep + kstep, voffB);
;         PG8_WAIT_V(6); PG8_BAR;
.LBB0_518:
	s_lshl_b32 s10, s10, 5
	s_and_b32 s49, s10, 0x60
	s_mov_b64 s[10:11], 0x80
	s_add_i32 m0, s14, 0x18000
	v_lshl_add_u64 v[6:7], v[6:7], 0, s[10:11]
	s_lshl_b32 s48, s5, 13
	s_lshl_b32 s60, s49, 7
	global_load_lds_dwordx4 v[6:7], off
	v_lshl_add_u64 v[4:5], v[4:5], 0, s[10:11]
	s_add_i32 m0, s14, 0x1a000
	s_add_i32 s76, s14, 0x8000
	s_add_i32 s77, s14, 0xa000
	global_load_lds_dwordx4 v[4:5], off
	v_lshl_add_u64 v[0:1], v[0:1], 0, s[10:11]
	s_mov_b32 m0, s76
	s_add_u32 s44, s72, 0x80080
	global_load_lds_dwordx4 v[0:1], off
	v_lshl_add_u64 v[0:1], v[2:3], 0, s[10:11]
	s_mov_b32 m0, s77
	s_addc_u32 s45, s73, 0
	global_load_lds_dwordx4 v[0:1], off
	s_add_i32 m0, s14, 0x1c000
	v_lshl_add_u64 v[0:1], s[44:45], 0, v[130:131]
	global_load_lds_dwordx4 v[0:1], off
	v_lshl_add_u64 v[0:1], s[44:45], 0, v[134:135]
	s_add_i32 m0, s14, 0x1e000
	s_cmpk_lt_u32 s25, 0x100
	global_load_lds_dwordx4 v[0:1], off
	s_cmp_lg_u32 s5, 1
	s_cbranch_scc1 .Lgp_skip_4
	s_barrier
.Lgp_skip_4:
	s_cmpk_lt_u32 s25, 0x100
	s_waitcnt vmcnt(8)
	s_barrier
	v_lshrrev_b32_e32 v1, 1, v8
	v_and_b32_e32 v1, 24, v1
	v_and_b32_e32 v0, 15, v8
	v_lshlrev_b32_e32 v2, 1, v1
	v_lshl_or_b32 v146, s5, 6, v0
	v_lshl_or_b32 v0, v0, 6, v2
	v_lshlrev_b32_e32 v2, 2, v8
	v_and_b32_e32 v2, 32, v2
	v_bitop3_b32 v3, v0, s48, v2 bitop3:0xde
	v_bitop3_b32 v147, v0, s60, v2 bitop3:0xde
	v_lshlrev_b32_e32 v0, 15, v9
	v_and_b32_e32 v0, 0xffff0000, v0
	v_or_b32_e32 v148, s49, v1
	v_lshl_add_u32 v0, v10, 12, v0
	v_and_b32_e32 v1, 1, v9
	v_lshl_or_b32 v0, v1, 6, v0
	v_lshl_add_u32 v136, v11, 1, v0
	v_lshlrev_b32_e32 v0, 15, v12
	v_and_b32_e32 v0, 0xffff0000, v0
	s_waitcnt vmcnt(6)
	v_lshl_add_u32 v0, v13, 12, v0
	v_and_b32_e32 v1, 1, v12
	s_cselect_b64 s[44:45], -1, 0
	v_lshl_or_b32 v0, v1, 6, v0
	s_add_i32 s80, 0, 0x10000
	s_add_i32 s81, 0, 0x14000
	s_sext_i32_i8 s24, s4
	s_ashr_i32 s78, s56, 31
	s_mov_b32 s79, s56
	v_mov_b32_e32 v137, v131
	v_lshl_add_u32 v138, v14, 1, v0
	v_mov_b32_e32 v139, v131
	v_mov_b64_e32 v[140:141], 0x400
	v_mov_b64_e32 v[142:143], 0x3ff
	v_add_u32_e32 v149, s80, v147
	v_add_u32_e32 v150, s81, v147
	v_add_u32_e32 v151, 0, v3
	s_mov_b64 s[48:49], 0x2c0000
	s_mov_b32 s82, 0x2c0000
	s_barrier
	s_branch .LBB0_521

; #define PG8_STAGE(bufoff, gbase, voff) do { _Pragma("unroll") for (int _i = 0; _i < 2; ++_i) \
;         __builtin_amdgcn_global_load_lds((const unsigned*)((const char*)(gbase) + (voff)[_i]), (PG8_LAS unsigned*)(lds + (bufoff) + ldsw + _i * 8192), 16, 0, 0); } while (0)
; #define PG8_WAIT_V(n) asm volatile("s_waitcnt vmcnt(" #n ")" ::: "memory")
; #define PG8_BAR __builtin_amdgcn_s_barrier()
; template <class Epi, class Sched, bool ALIGN_EPI = false, bool SP2 = false>
; __device__ __forceinline__ void gemm_phase(PG8_LAS unsigned char* lds, const Gemm g, const Sched& S, const Epi& E) {
;     ...
;     if constexpr (SP2) {
;         PG8_STAGE(PG8_SB(0, 0), cB, voffB); PG8_STAGE(PG8_SB(0, 1), cB + hstep, voffB); PG8_STAGE(PG8_SA(0, 0), cA, voffA); PG8_STAGE(PG8_SA(0, 1), cA + hstep, voffA);
;         if (wr == 1) PG8_BAR;
;         PG8_WAIT_V(2); PG8_BAR;
;         PG8_STAGE(PG8_SB(1, 0), cB + kstep, voffB); PG8_STAGE(PG8_SA(1, 0), cA + kstep, voffA); PG8_STAGE(PG8_SB(1, 1), cB + hstep + kstep, voffB);
;         PG8_WAIT_V(6); PG8_BAR;
.LBB0_594:
	s_lshl_b32 s7, s7, 5
	s_mov_b64 s[10:11], 0x80
	s_and_b32 s7, s7, 0x60
	s_add_i32 m0, s4, 0x18000
	v_lshl_add_u64 v[6:7], v[6:7], 0, s[10:11]
	s_lshl_b32 s49, s48, 13
	s_lshl_b32 s62, s7, 7
	global_load_lds_dwordx4 v[6:7], off
	v_lshl_add_u64 v[4:5], v[4:5], 0, s[10:11]
	s_add_i32 m0, s4, 0x1a000
	s_add_i32 s35, s4, 0x8000
	s_add_i32 s71, s4, 0xa000
	global_load_lds_dwordx4 v[4:5], off
	v_lshl_add_u64 v[0:1], v[0:1], 0, s[10:11]
	s_mov_b32 m0, s35
	s_add_u32 s60, s74, 0x200080
	global_load_lds_dwordx4 v[0:1], off
	v_lshl_add_u64 v[0:1], v[2:3], 0, s[10:11]
	s_mov_b32 m0, s71
	s_addc_u32 s61, s75, 0
	global_load_lds_dwordx4 v[0:1], off
	s_add_i32 m0, s4, 0x1c000
	v_lshl_add_u64 v[0:1], s[60:61], 0, v[170:171]
	global_load_lds_dwordx4 v[0:1], off
	v_lshl_add_u64 v[0:1], s[60:61], 0, v[174:175]
	s_add_i32 m0, s4, 0x1e000
	s_cmpk_lt_u32 s25, 0x100
	global_load_lds_dwordx4 v[0:1], off
	s_cmp_lg_u32 s48, 1
	s_cbranch_scc1 .Lgp_skip_5
	s_barrier
.Lgp_skip_5:
	s_cmpk_lt_u32 s25, 0x100
	s_waitcnt vmcnt(8)
	s_barrier
	v_lshrrev_b32_e32 v1, 1, v8
	v_and_b32_e32 v1, 24, v1
	v_and_b32_e32 v0, 15, v8
	v_lshlrev_b32_e32 v2, 1, v1
	v_lshl_or_b32 v199, s48, 6, v0
	v_lshl_or_b32 v0, v0, 6, v2
	v_lshlrev_b32_e32 v2, 2, v8
	v_and_b32_e32 v2, 32, v2
	v_bitop3_b32 v3, v0, s49, v2 bitop3:0xde
	v_bitop3_b32 v200, v0, s62, v2 bitop3:0xde
	v_lshlrev_b32_e32 v0, 17, v9
	v_and_b32_e32 v0, 0xfffc0000, v0
	v_or_b32_e32 v201, s7, v1
	v_lshl_add_u32 v0, v10, 14, v0
	v_and_b32_e32 v1, 1, v9
	v_lshl_or_b32 v0, v1, 6, v0
	v_lshl_add_u32 v176, v11, 1, v0
	v_lshlrev_b32_e32 v0, 17, v12
	v_and_b32_e32 v0, 0xfffc0000, v0
	s_waitcnt vmcnt(6)
	v_lshl_add_u32 v0, v13, 14, v0
	v_and_b32_e32 v1, 1, v12
	s_cselect_b64 s[48:49], -1, 0
	v_lshl_or_b32 v0, v1, 6, v0
	s_add_i32 s80, 0, 0x10000
	s_add_i32 s81, 0, 0x14000
	s_sext_i32_i8 s24, s6
	s_ashr_i32 s78, s56, 31
	s_mov_b32 s79, s56
	v_mov_b32_e32 v177, v171
	v_lshl_add_u32 v178, v14, 1, v0
	v_mov_b32_e32 v179, v171
	v_mov_b64_e32 v[180:181], 0x100
	v_mov_b64_e32 v[182:183], 0xff
	v_add_u32_e32 v202, s80, v200
	v_add_u32_e32 v203, s81, v200
	v_add_u32_e32 v204, 0, v3
	s_mov_b64 s[60:61], 0xb0000
	s_barrier
	s_branch .LBB0_597

; #define PG8_STAGE(bufoff, gbase, voff) do { _Pragma("unroll") for (int _i = 0; _i < 2; ++_i) \
;         __builtin_amdgcn_global_load_lds((const unsigned*)((const char*)(gbase) + (voff)[_i]), (PG8_LAS unsigned*)(lds + (bufoff) + ldsw + _i * 8192), 16, 0, 0); } while (0)
; #define PG8_WAIT_V(n) asm volatile("s_waitcnt vmcnt(" #n ")" ::: "memory")
; #define PG8_BAR __builtin_amdgcn_s_barrier()
; template <class Epi, class Sched, bool ALIGN_EPI = false, bool SP2 = false>
; __device__ __forceinline__ void gemm_phase(PG8_LAS unsigned char* lds, const Gemm g, const Sched& S, const Epi& E) {
;     ...
;     if constexpr (SP2) {
;         PG8_STAGE(PG8_SB(0, 0), cB, voffB); PG8_STAGE(PG8_SB(0, 1), cB + hstep, voffB); PG8_STAGE(PG8_SA(0, 0), cA, voffA); PG8_STAGE(PG8_SA(0, 1), cA + hstep, voffA);
;         if (wr == 1) PG8_BAR;
;         PG8_WAIT_V(2); PG8_BAR;
;         PG8_STAGE(PG8_SB(1, 0), cB + kstep, voffB); PG8_STAGE(PG8_SA(1, 0), cA + kstep, voffA); PG8_STAGE(PG8_SB(1, 1), cB + hstep + kstep, voffB);
;         PG8_WAIT_V(6); PG8_BAR;
.LBB0_725:
	s_lshl_b32 s10, s10, 5
	s_and_b32 s48, s10, 0x60
	s_mov_b64 s[10:11], 0x80
	s_add_i32 m0, s4, 0x18000
	v_lshl_add_u64 v[6:7], v[6:7], 0, s[10:11]
	s_lshl_b32 s35, s7, 6
	s_lshl_b32 s7, s7, 13
	s_lshl_b32 s49, s48, 7
	global_load_lds_dwordx4 v[6:7], off
	v_lshl_add_u64 v[4:5], v[4:5], 0, s[10:11]
	s_add_i32 m0, s4, 0x1a000
	s_add_i32 s67, s4, 0x8000
	s_add_i32 s74, s4, 0xa000
	global_load_lds_dwordx4 v[4:5], off
	v_lshl_add_u64 v[0:1], v[0:1], 0, s[10:11]
	s_mov_b32 m0, s67
	s_add_u32 s38, s70, 0x80080
	global_load_lds_dwordx4 v[0:1], off
	v_lshl_add_u64 v[0:1], v[2:3], 0, s[10:11]
	s_mov_b32 m0, s74
	s_addc_u32 s39, s71, 0
	global_load_lds_dwordx4 v[0:1], off
	s_add_i32 m0, s4, 0x1c000
	v_lshl_add_u64 v[0:1], s[38:39], 0, v[130:131]
	global_load_lds_dwordx4 v[0:1], off
	v_lshl_add_u64 v[0:1], s[38:39], 0, v[134:135]
	s_add_i32 m0, s4, 0x1e000
	v_and_b32_e32 v149, 15, v8
	global_load_lds_dwordx4 v[0:1], off
	s_cmp_eq_u64 s[8:9], 0
	s_cbranch_scc1 .Lgp_skip_6
	s_barrier
.Lgp_skip_6:
	s_waitcnt vmcnt(8)
	s_barrier
	v_lshrrev_b32_e32 v0, 1, v8
	v_and_b32_e32 v0, 24, v0
	v_lshlrev_b32_e32 v1, 1, v0
	v_lshlrev_b32_e32 v2, 2, v8
	v_lshl_or_b32 v1, v149, 6, v1
	v_and_b32_e32 v2, 32, v2
	v_bitop3_b32 v3, v1, s7, v2 bitop3:0xde
	v_bitop3_b32 v150, v1, s49, v2 bitop3:0xde
	v_lshlrev_b32_e32 v1, 15, v9
	v_and_b32_e32 v1, 0xffff0000, v1
	v_lshl_add_u32 v1, v10, 12, v1
	v_and_b32_e32 v2, 1, v9
	v_lshl_or_b32 v1, v2, 6, v1
	v_lshl_add_u32 v138, v11, 1, v1
	v_lshlrev_b32_e32 v1, 15, v12
	v_and_b32_e32 v1, 0xffff0000, v1
	s_waitcnt vmcnt(6)
	s_cmpk_lt_u32 s25, 0x100
	v_lshl_add_u32 v1, v13, 12, v1
	v_and_b32_e32 v2, 1, v12
	s_cselect_b64 s[38:39], -1, 0
	v_or_b32_e32 v0, s48, v0
	v_lshl_or_b32 v1, v2, 6, v1
	s_add_i32 s77, 0, 0x10000
	s_add_i32 s78, 0, 0x14000
	s_sext_i32_i8 s24, s6
	s_ashr_i32 s75, s56, 31
	s_mov_b32 s76, s56
	v_mov_b32_e32 v139, v137
	v_lshl_add_u32 v140, v14, 1, v1
	v_mov_b32_e32 v141, v137
	v_mov_b64_e32 v[142:143], 0x400
	v_mov_b64_e32 v[144:145], 0x3ff
	v_add_u32_e32 v151, s77, v150
	v_add_u32_e32 v152, s78, v150
	v_add_u32_e32 v153, 0, v3
	v_lshlrev_b32_e32 v136, 1, v0
	v_mov_b32_e32 v154, 0x3e38aa3b
	v_mov_b32_e32 v155, 0xfcf
	s_barrier
	s_branch .LBB0_728

; #define PG8_STAGE(bufoff, gbase, voff) do { _Pragma("unroll") for (int _i = 0; _i < 2; ++_i) \
;         __builtin_amdgcn_global_load_lds((const unsigned*)((const char*)(gbase) + (voff)[_i]), (PG8_LAS unsigned*)(lds + (bufoff) + ldsw + _i * 8192), 16, 0, 0); } while (0)
; #define PG8_WAIT_V(n) asm volatile("s_waitcnt vmcnt(" #n ")" ::: "memory")
; #define PG8_BAR __builtin_amdgcn_s_barrier()
; template <class Epi, class Sched, bool ALIGN_EPI = false, bool SP2 = false>
; __device__ __forceinline__ void gemm_phase(PG8_LAS unsigned char* lds, const Gemm g, const Sched& S, const Epi& E) {
;     ...
;     if constexpr (SP2) {
;         PG8_STAGE(PG8_SB(0, 0), cB, voffB); PG8_STAGE(PG8_SB(0, 1), cB + hstep, voffB); PG8_STAGE(PG8_SA(0, 0), cA, voffA); PG8_STAGE(PG8_SA(0, 1), cA + hstep, voffA);
;         if (wr == 1) PG8_BAR;
;         PG8_WAIT_V(2); PG8_BAR;
;         PG8_STAGE(PG8_SB(1, 0), cB + kstep, voffB); PG8_STAGE(PG8_SA(1, 0), cA + kstep, voffA); PG8_STAGE(PG8_SB(1, 1), cB + hstep + kstep, voffB);
;         PG8_WAIT_V(6); PG8_BAR;
.LBB0_749:
	s_lshl_b32 s48, s12, 5
	s_mov_b64 s[12:13], 0x80
	s_and_b32 s67, s48, 0x60
	s_add_i32 m0, s6, 0x18000
	v_lshl_add_u64 v[6:7], v[6:7], 0, s[12:13]
	s_lshl_b32 s35, s9, 6
	s_lshl_b32 s9, s9, 13
	s_lshl_b32 s49, s67, 7
	global_load_lds_dwordx4 v[6:7], off
	v_lshl_add_u64 v[4:5], v[4:5], 0, s[12:13]
	s_add_i32 m0, s6, 0x1a000
	s_add_i32 s74, s6, 0x8000
	s_add_i32 s75, s6, 0xa000
	global_load_lds_dwordx4 v[4:5], off
	v_lshl_add_u64 v[0:1], v[0:1], 0, s[12:13]
	s_mov_b32 m0, s74
	s_add_u32 s46, s70, 0x80080
	global_load_lds_dwordx4 v[0:1], off
	v_lshl_add_u64 v[0:1], v[2:3], 0, s[12:13]
	s_mov_b32 m0, s75
	s_addc_u32 s47, s71, 0
	global_load_lds_dwordx4 v[0:1], off
	s_add_i32 m0, s6, 0x1c000
	v_lshl_add_u64 v[0:1], s[46:47], 0, v[130:131]
	global_load_lds_dwordx4 v[0:1], off
	v_lshl_add_u64 v[0:1], s[46:47], 0, v[134:135]
	s_add_i32 m0, s6, 0x1e000
	v_lshlrev_b32_e32 v3, 2, v8
	global_load_lds_dwordx4 v[0:1], off
	s_cmp_eq_u64 s[10:11], 0
	s_cbranch_scc1 .Lgp_skip_7
	s_barrier
.Lgp_skip_7:
	s_waitcnt vmcnt(8)
	s_barrier
	v_lshrrev_b32_e32 v1, 1, v8
	v_and_b32_e32 v1, 24, v1
	v_and_b32_e32 v0, 15, v8
	v_lshlrev_b32_e32 v2, 1, v1
	v_lshl_or_b32 v2, v0, 6, v2
	v_and_or_b32 v147, s35, 64, v0
	v_and_or_b32 v0, s48, 32, v1
	v_lshlrev_b32_e32 v0, 1, v0
	v_mov_b32_e32 v1, v131
	v_lshl_add_u64 v[136:137], s[38:39], 0, v[0:1]
	v_lshlrev_b32_e32 v0, 15, v9
	v_and_b32_e32 v0, 0xffff0000, v0
	v_lshl_add_u32 v0, v10, 12, v0
	v_and_b32_e32 v1, 1, v9
	v_lshl_or_b32 v0, v1, 6, v0
	v_lshl_add_u32 v138, v11, 1, v0
	v_lshlrev_b32_e32 v0, 15, v12
	v_and_b32_e32 v0, 0xffff0000, v0
	v_and_b32_e32 v3, 32, v3
	s_waitcnt vmcnt(6)
	s_cmpk_lt_u32 s25, 0x100
	v_lshl_add_u32 v0, v13, 12, v0
	v_and_b32_e32 v1, 1, v12
	v_bitop3_b32 v4, v2, s9, v3 bitop3:0xde
	v_bitop3_b32 v146, v2, s49, v3 bitop3:0xde
	s_cselect_b64 s[46:47], -1, 0
	v_lshl_or_b32 v0, v1, 6, v0
	s_add_i32 s78, 0, 0x10000
	s_add_i32 s79, 0, 0x14000
	s_sext_i32_i16 s24, s8
	v_or_b32_e32 v148, 0x2000, v147
	s_ashr_i32 s76, s56, 31
	s_mov_b32 s77, s56
	v_mov_b32_e32 v139, v131
	v_lshl_add_u32 v140, v14, 1, v0
	v_mov_b32_e32 v141, v131
	v_mov_b64_e32 v[142:143], 0x200
	v_mov_b64_e32 v[144:145], 0x1ff
	v_add_u32_e32 v149, s78, v146
	v_add_u32_e32 v150, s79, v146
	v_add_u32_e32 v151, 0, v4
	s_barrier
	s_branch .LBB0_752

; #define PG8_STAGE(bufoff, gbase, voff) do { _Pragma("unroll") for (int _i = 0; _i < 2; ++_i) \
;         __builtin_amdgcn_global_load_lds((const unsigned*)((const char*)(gbase) + (voff)[_i]), (PG8_LAS unsigned*)(lds + (bufoff) + ldsw + _i * 8192), 16, 0, 0); } while (0)
; #define PG8_WAIT_V(n) asm volatile("s_waitcnt vmcnt(" #n ")" ::: "memory")
; #define PG8_BAR __builtin_amdgcn_s_barrier()
; template <class Epi, class Sched, bool ALIGN_EPI = false, bool SP2 = false>
; __device__ __forceinline__ void gemm_phase(PG8_LAS unsigned char* lds, const Gemm g, const Sched& S, const Epi& E) {
;     ...
;     if constexpr (SP2) {
;         PG8_STAGE(PG8_SB(0, 0), cB, voffB); PG8_STAGE(PG8_SB(0, 1), cB + hstep, voffB); PG8_STAGE(PG8_SA(0, 0), cA, voffA); PG8_STAGE(PG8_SA(0, 1), cA + hstep, voffA);
;         if (wr == 1) PG8_BAR;
;         PG8_WAIT_V(2); PG8_BAR;
;         PG8_STAGE(PG8_SB(1, 0), cB + kstep, voffB); PG8_STAGE(PG8_SA(1, 0), cA + kstep, voffA); PG8_STAGE(PG8_SB(1, 1), cB + hstep + kstep, voffB);
;         PG8_WAIT_V(6); PG8_BAR;
.LBB0_1043:
	s_lshl_b32 s7, s7, 5
	s_mov_b64 s[12:13], 0x80
	s_and_b32 s7, s7, 0x60
	s_add_i32 m0, s3, 0x18000
	v_lshl_add_u64 v[6:7], v[6:7], 0, s[12:13]
	s_lshl_b32 s20, s17, 13
	s_lshl_b32 s21, s7, 7
	global_load_lds_dwordx4 v[6:7], off
	v_lshl_add_u64 v[2:3], v[2:3], 0, s[12:13]
	s_add_i32 m0, s3, 0x1a000
	s_add_i32 s33, s3, 0x8000
	s_add_i32 s35, s3, 0xa000
	global_load_lds_dwordx4 v[2:3], off
	v_lshl_add_u64 v[0:1], v[0:1], 0, s[12:13]
	s_mov_b32 m0, s33
	s_add_u32 s18, s62, 0x80080
	global_load_lds_dwordx4 v[0:1], off
	v_lshl_add_u64 v[0:1], v[4:5], 0, s[12:13]
	s_mov_b32 m0, s35
	s_addc_u32 s19, s63, 0
	global_load_lds_dwordx4 v[0:1], off
	s_add_i32 m0, s3, 0x1c000
	v_lshl_add_u64 v[0:1], s[18:19], 0, v[170:171]
	global_load_lds_dwordx4 v[0:1], off
	v_lshl_add_u64 v[0:1], s[18:19], 0, v[174:175]
	s_add_i32 m0, s3, 0x1e000
	s_cmpk_lt_u32 s16, 0x100
	global_load_lds_dwordx4 v[0:1], off
	s_cmp_lg_u32 s17, 1
	s_cbranch_scc1 .Lgp_skip_8
	s_barrier
.Lgp_skip_8:
	s_cmpk_lt_u32 s16, 0x100
	s_waitcnt vmcnt(8)
	s_barrier
	v_lshrrev_b32_e32 v1, 1, v8
	v_and_b32_e32 v1, 24, v1
	v_and_b32_e32 v0, 15, v8
	v_lshlrev_b32_e32 v2, 1, v1
	v_lshl_or_b32 v199, s17, 6, v0
	v_lshl_or_b32 v0, v0, 6, v2
	v_lshlrev_b32_e32 v2, 2, v8
	v_and_b32_e32 v2, 32, v2
	v_bitop3_b32 v3, v0, s20, v2 bitop3:0xde
	v_bitop3_b32 v200, v0, s21, v2 bitop3:0xde
	v_lshlrev_b32_e32 v0, 15, v9
	v_and_b32_e32 v0, 0xffff0000, v0
	v_or_b32_e32 v201, s7, v1
	v_lshl_add_u32 v0, v10, 12, v0
	v_and_b32_e32 v1, 1, v9
	v_lshl_or_b32 v0, v1, 6, v0
	v_lshl_add_u32 v176, v11, 1, v0
	v_lshlrev_b32_e32 v0, 15, v12
	v_and_b32_e32 v0, 0xffff0000, v0
	s_waitcnt vmcnt(6)
	v_lshl_add_u32 v0, v13, 12, v0
	v_and_b32_e32 v1, 1, v12
	s_cselect_b64 s[16:17], -1, 0
	v_lshl_or_b32 v0, v1, 6, v0
	s_add_i32 s67, 0, 0x10000
	s_add_i32 s68, 0, 0x14000
	s_sext_i32_i8 s24, s6
	s_ashr_i32 s51, s56, 31
	s_mov_b32 s66, s56
	v_mov_b32_e32 v177, v171
	v_lshl_add_u32 v178, v14, 1, v0
	v_mov_b32_e32 v179, v171
	v_mov_b64_e32 v[180:181], 0x200
	v_mov_b64_e32 v[182:183], 0x1ff
	v_add_u32_e32 v202, s67, v200
	v_add_u32_e32 v203, s68, v200
	v_add_u32_e32 v204, 0, v3
	s_mov_b64 s[18:19], 0x90000
	s_mov_b64 s[20:21], 0xa0000
	s_mov_b64 s[22:23], 0xb0000
	s_barrier
	s_branch .LBB0_1046

; #define PG8_STAGE(bufoff, gbase, voff) do { _Pragma("unroll") for (int _i = 0; _i < 2; ++_i) \
;         __builtin_amdgcn_global_load_lds((const unsigned*)((const char*)(gbase) + (voff)[_i]), (PG8_LAS unsigned*)(lds + (bufoff) + ldsw + _i * 8192), 16, 0, 0); } while (0)
; #define PG8_WAIT_V(n) asm volatile("s_waitcnt vmcnt(" #n ")" ::: "memory")
; #define PG8_BAR __builtin_amdgcn_s_barrier()
; template <class Epi, class Sched, bool ALIGN_EPI = false, bool SP2 = false>
; __device__ __forceinline__ void gemm_phase(PG8_LAS unsigned char* lds, const Gemm g, const Sched& S, const Epi& E) {
;     ...
;     if constexpr (SP2) {
;         PG8_STAGE(PG8_SB(0, 0), cB, voffB); PG8_STAGE(PG8_SB(0, 1), cB + hstep, voffB); PG8_STAGE(PG8_SA(0, 0), cA, voffA); PG8_STAGE(PG8_SA(0, 1), cA + hstep, voffA);
;         if (wr == 1) PG8_BAR;
;         PG8_WAIT_V(2); PG8_BAR;
;         PG8_STAGE(PG8_SB(1, 0), cB + kstep, voffB); PG8_STAGE(PG8_SA(1, 0), cA + kstep, voffA); PG8_STAGE(PG8_SB(1, 1), cB + hstep + kstep, voffB);
;         PG8_WAIT_V(6); PG8_BAR;
.LBB0_1174:
	s_lshl_b32 s10, s10, 5
	s_and_b32 s18, s10, 0x60
	s_mov_b64 s[10:11], 0x80
	s_add_i32 m0, s3, 0x18000
	v_lshl_add_u64 v[6:7], v[6:7], 0, s[10:11]
	s_lshl_b32 s13, s7, 13
	s_lshl_b32 s19, s18, 7
	global_load_lds_dwordx4 v[6:7], off
	v_lshl_add_u64 v[4:5], v[4:5], 0, s[10:11]
	s_add_i32 m0, s3, 0x1a000
	s_add_i32 s49, s3, 0x8000
	s_add_i32 s62, s3, 0xa000
	global_load_lds_dwordx4 v[4:5], off
	v_lshl_add_u64 v[0:1], v[0:1], 0, s[10:11]
	s_mov_b32 m0, s49
	s_add_u32 s16, s58, 0x80080
	global_load_lds_dwordx4 v[0:1], off
	v_lshl_add_u64 v[0:1], v[2:3], 0, s[10:11]
	s_mov_b32 m0, s62
	s_addc_u32 s17, s59, 0
	global_load_lds_dwordx4 v[0:1], off
	s_add_i32 m0, s3, 0x1c000
	v_lshl_add_u64 v[0:1], s[16:17], 0, v[130:131]
	global_load_lds_dwordx4 v[0:1], off
	v_lshl_add_u64 v[0:1], s[16:17], 0, v[134:135]
	s_add_i32 m0, s3, 0x1e000
	s_cmpk_lt_u32 s12, 0x100
	global_load_lds_dwordx4 v[0:1], off
	s_cmp_lg_u32 s7, 1
	s_cbranch_scc1 .Lgp_skip_9
	s_barrier
.Lgp_skip_9:
	s_cmpk_lt_u32 s12, 0x100
	s_waitcnt vmcnt(8)
	s_barrier
	v_lshrrev_b32_e32 v1, 1, v8
	v_and_b32_e32 v1, 24, v1
	v_and_b32_e32 v0, 15, v8
	v_lshlrev_b32_e32 v2, 1, v1
	v_lshl_or_b32 v146, s7, 6, v0
	v_lshl_or_b32 v0, v0, 6, v2
	v_lshlrev_b32_e32 v2, 2, v8
	v_and_b32_e32 v2, 32, v2
	v_bitop3_b32 v3, v0, s13, v2 bitop3:0xde
	v_bitop3_b32 v147, v0, s19, v2 bitop3:0xde
	v_lshlrev_b32_e32 v0, 15, v9
	v_and_b32_e32 v0, 0xffff0000, v0
	v_or_b32_e32 v148, s18, v1
	v_lshl_add_u32 v0, v10, 12, v0
	v_and_b32_e32 v1, 1, v9
	v_lshl_or_b32 v0, v1, 6, v0
	v_lshl_add_u32 v136, v11, 1, v0
	v_lshlrev_b32_e32 v0, 15, v12
	v_and_b32_e32 v0, 0xffff0000, v0
	s_waitcnt vmcnt(6)
	v_lshl_add_u32 v0, v13, 12, v0
	v_and_b32_e32 v1, 1, v12
	s_cselect_b64 s[12:13], -1, 0
	v_lshl_or_b32 v0, v1, 6, v0
	s_add_i32 s65, 0, 0x10000
	s_add_i32 s66, 0, 0x14000
	s_sext_i32_i8 s24, s6
	s_ashr_i32 s63, s56, 31
	s_mov_b32 s64, s56
	v_mov_b32_e32 v137, v131
	v_lshl_add_u32 v138, v14, 1, v0
	v_mov_b32_e32 v139, v131
	v_mov_b64_e32 v[140:141], 0x400
	v_mov_b64_e32 v[142:143], 0x3ff
	v_add_u32_e32 v149, s65, v147
	v_add_u32_e32 v150, s66, v147
	v_add_u32_e32 v151, 0, v3
	s_mov_b64 s[16:17], 0x200000
	s_mov_b32 s67, 0x200000
	s_mov_b64 s[18:19], 0x240000
	s_mov_b32 s68, 0x240000
	s_mov_b64 s[20:21], 0x280000
	s_mov_b32 s69, 0x280000
	s_mov_b64 s[22:23], 0x2c0000
	s_mov_b32 s70, 0x2c0000
	s_barrier
	s_branch .LBB0_1177

; #define PG8_STAGE(bufoff, gbase, voff) do { _Pragma("unroll") for (int _i = 0; _i < 2; ++_i) \
;         __builtin_amdgcn_global_load_lds((const unsigned*)((const char*)(gbase) + (voff)[_i]), (PG8_LAS unsigned*)(lds + (bufoff) + ldsw + _i * 8192), 16, 0, 0); } while (0)
; #define PG8_WAIT_V(n) asm volatile("s_waitcnt vmcnt(" #n ")" ::: "memory")
; #define PG8_BAR __builtin_amdgcn_s_barrier()
; template <class Epi, class Sched, bool ALIGN_EPI = false, bool SP2 = false>
; __device__ __forceinline__ void gemm_phase(PG8_LAS unsigned char* lds, const Gemm g, const Sched& S, const Epi& E) {
;     ...
;     if constexpr (SP2) {
;         PG8_STAGE(PG8_SB(0, 0), cB, voffB); PG8_STAGE(PG8_SB(0, 1), cB + hstep, voffB); PG8_STAGE(PG8_SA(0, 0), cA, voffA); PG8_STAGE(PG8_SA(0, 1), cA + hstep, voffA);
;         if (wr == 1) PG8_BAR;
;         PG8_WAIT_V(2); PG8_BAR;
;         PG8_STAGE(PG8_SB(1, 0), cB + kstep, voffB); PG8_STAGE(PG8_SA(1, 0), cA + kstep, voffA); PG8_STAGE(PG8_SB(1, 1), cB + hstep + kstep, voffB);
;         PG8_WAIT_V(6); PG8_BAR;
.LBB0_1250:
	s_lshl_b32 s7, s7, 5
	s_mov_b64 s[10:11], 0x80
	s_and_b32 s7, s7, 0x60
	s_add_i32 m0, s14, 0x18000
	v_lshl_add_u64 v[6:7], v[6:7], 0, s[10:11]
	s_lshl_b32 s18, s13, 13
	s_lshl_b32 s19, s7, 7
	global_load_lds_dwordx4 v[6:7], off
	v_lshl_add_u64 v[4:5], v[4:5], 0, s[10:11]
	s_add_i32 m0, s14, 0x1a000
	s_add_i32 s63, s14, 0x8000
	s_add_i32 s64, s14, 0xa000
	global_load_lds_dwordx4 v[4:5], off
	v_lshl_add_u64 v[0:1], v[0:1], 0, s[10:11]
	s_mov_b32 m0, s63
	s_add_u32 s16, s58, 0x200080
	global_load_lds_dwordx4 v[0:1], off
	v_lshl_add_u64 v[0:1], v[2:3], 0, s[10:11]
	s_mov_b32 m0, s64
	s_addc_u32 s17, s59, 0
	global_load_lds_dwordx4 v[0:1], off
	s_add_i32 m0, s14, 0x1c000
	v_lshl_add_u64 v[0:1], s[16:17], 0, v[170:171]
	global_load_lds_dwordx4 v[0:1], off
	v_lshl_add_u64 v[0:1], s[16:17], 0, v[174:175]
	s_add_i32 m0, s14, 0x1e000
	s_cmpk_lt_u32 s12, 0x100
	global_load_lds_dwordx4 v[0:1], off
	s_cmp_lg_u32 s13, 1
	s_cbranch_scc1 .Lgp_skip_10
	s_barrier
.Lgp_skip_10:
	s_cmpk_lt_u32 s12, 0x100
	s_waitcnt vmcnt(8)
	s_barrier
	v_lshrrev_b32_e32 v1, 1, v8
	v_and_b32_e32 v1, 24, v1
	v_and_b32_e32 v0, 15, v8
	v_lshlrev_b32_e32 v2, 1, v1
	v_lshl_or_b32 v199, s13, 6, v0
	v_lshl_or_b32 v0, v0, 6, v2
	v_lshlrev_b32_e32 v2, 2, v8
	v_and_b32_e32 v2, 32, v2
	v_bitop3_b32 v3, v0, s18, v2 bitop3:0xde
	v_bitop3_b32 v200, v0, s19, v2 bitop3:0xde
	v_lshlrev_b32_e32 v0, 17, v9
	v_and_b32_e32 v0, 0xfffc0000, v0
	v_or_b32_e32 v201, s7, v1
	v_lshl_add_u32 v0, v10, 14, v0
	v_and_b32_e32 v1, 1, v9
	v_lshl_or_b32 v0, v1, 6, v0
	v_lshl_add_u32 v176, v11, 1, v0
	v_lshlrev_b32_e32 v0, 17, v12
	v_and_b32_e32 v0, 0xfffc0000, v0
	s_waitcnt vmcnt(6)
	v_lshl_add_u32 v0, v13, 14, v0
	v_and_b32_e32 v1, 1, v12
	s_cselect_b64 s[12:13], -1, 0
	v_lshl_or_b32 v0, v1, 6, v0
	s_add_i32 s67, 0, 0x10000
	s_add_i32 s68, 0, 0x14000
	s_sext_i32_i8 s24, s6
	s_ashr_i32 s65, s56, 31
	s_mov_b32 s66, s56
	v_mov_b32_e32 v177, v171
	v_lshl_add_u32 v178, v14, 1, v0
	v_mov_b32_e32 v179, v171
	v_mov_b64_e32 v[180:181], 0x100
	v_mov_b64_e32 v[182:183], 0xff
	v_add_u32_e32 v202, s67, v200
	v_add_u32_e32 v203, s68, v200
	v_add_u32_e32 v204, 0, v3
	s_mov_b64 s[16:17], 0x80000
	s_mov_b64 s[18:19], 0x90000
	s_mov_b64 s[20:21], 0xa0000
	s_mov_b64 s[22:23], 0xb0000
	s_barrier
	s_branch .LBB0_1253

; #define PG8_STAGE(bufoff, gbase, voff) do { _Pragma("unroll") for (int _i = 0; _i < 2; ++_i) \
;         __builtin_amdgcn_global_load_lds((const unsigned*)((const char*)(gbase) + (voff)[_i]), (PG8_LAS unsigned*)(lds + (bufoff) + ldsw + _i * 8192), 16, 0, 0); } while (0)
; #define PG8_WAIT_V(n) asm volatile("s_waitcnt vmcnt(" #n ")" ::: "memory")
; #define PG8_BAR __builtin_amdgcn_s_barrier()
; template <class Epi, class Sched, bool ALIGN_EPI = false, bool SP2 = false>
; __device__ __forceinline__ void gemm_phase(PG8_LAS unsigned char* lds, const Gemm g, const Sched& S, const Epi& E) {
;     ...
;     if constexpr (SP2) {
;         PG8_STAGE(PG8_SB(0, 0), cB, voffB); PG8_STAGE(PG8_SB(0, 1), cB + hstep, voffB); PG8_STAGE(PG8_SA(0, 0), cA, voffA); PG8_STAGE(PG8_SA(0, 1), cA + hstep, voffA);
;         if (wr == 1) PG8_BAR;
;         PG8_WAIT_V(2); PG8_BAR;
;         PG8_STAGE(PG8_SB(1, 0), cB + kstep, voffB); PG8_STAGE(PG8_SA(1, 0), cA + kstep, voffA); PG8_STAGE(PG8_SB(1, 1), cB + hstep + kstep, voffB);
;         PG8_WAIT_V(6); PG8_BAR;
.LBB0_1326:
	s_lshl_b32 s10, s10, 5
	s_and_b32 s16, s10, 0x60
	s_mov_b64 s[10:11], 0x80
	s_add_i32 m0, s33, 0x18000
	v_lshl_add_u64 v[6:7], v[6:7], 0, s[10:11]
	s_lshl_b32 s13, s7, 13
	s_lshl_b32 s17, s16, 7
	global_load_lds_dwordx4 v[6:7], off
	v_lshl_add_u64 v[4:5], v[4:5], 0, s[10:11]
	s_add_i32 m0, s33, 0x1a000
	s_add_i32 s61, s33, 0x8000
	s_add_i32 s62, s33, 0xa000
	global_load_lds_dwordx4 v[4:5], off
	v_lshl_add_u64 v[0:1], v[0:1], 0, s[10:11]
	s_mov_b32 m0, s61
	s_add_u32 s14, s48, 0x80080
	global_load_lds_dwordx4 v[0:1], off
	v_lshl_add_u64 v[0:1], v[2:3], 0, s[10:11]
	s_mov_b32 m0, s62
	s_addc_u32 s15, s49, 0
	global_load_lds_dwordx4 v[0:1], off
	s_add_i32 m0, s33, 0x1c000
	v_lshl_add_u64 v[0:1], s[14:15], 0, v[130:131]
	global_load_lds_dwordx4 v[0:1], off
	v_lshl_add_u64 v[0:1], s[14:15], 0, v[134:135]
	s_add_i32 m0, s33, 0x1e000
	s_cmpk_lt_u32 s12, 0x100
	global_load_lds_dwordx4 v[0:1], off
	s_cmp_lg_u32 s7, 1
	s_cbranch_scc1 .Lgp_skip_11
	s_barrier
.Lgp_skip_11:
	s_cmpk_lt_u32 s12, 0x100
	s_waitcnt vmcnt(8)
	s_barrier
	v_lshrrev_b32_e32 v1, 1, v8
	v_and_b32_e32 v1, 24, v1
	v_and_b32_e32 v0, 15, v8
	v_lshlrev_b32_e32 v2, 1, v1
	v_lshl_or_b32 v146, s7, 6, v0
	v_lshl_or_b32 v0, v0, 6, v2
	v_lshlrev_b32_e32 v2, 2, v8
	v_and_b32_e32 v2, 32, v2
	v_bitop3_b32 v3, v0, s13, v2 bitop3:0xde
	v_bitop3_b32 v147, v0, s17, v2 bitop3:0xde
	v_lshlrev_b32_e32 v0, 15, v9
	v_and_b32_e32 v0, 0xffff0000, v0
	v_or_b32_e32 v148, s16, v1
	v_lshl_add_u32 v0, v10, 12, v0
	v_and_b32_e32 v1, 1, v9
	v_lshl_or_b32 v0, v1, 6, v0
	v_lshl_add_u32 v136, v11, 1, v0
	v_lshlrev_b32_e32 v0, 15, v12
	v_and_b32_e32 v0, 0xffff0000, v0
	s_waitcnt vmcnt(6)
	v_lshl_add_u32 v0, v13, 12, v0
	v_and_b32_e32 v1, 1, v12
	s_cselect_b64 s[12:13], -1, 0
	v_lshl_or_b32 v0, v1, 6, v0
	s_add_i32 s65, 0, 0x10000
	s_add_i32 s66, 0, 0x14000
	s_sext_i32_i8 s24, s6
	s_ashr_i32 s63, s56, 31
	s_mov_b32 s64, s56
	v_mov_b32_e32 v137, v131
	v_lshl_add_u32 v138, v14, 1, v0
	v_mov_b32_e32 v139, v131
	v_mov_b64_e32 v[140:141], 0x400
	v_mov_b64_e32 v[142:143], 0x3ff
	v_add_u32_e32 v149, s65, v147
	v_add_u32_e32 v150, s66, v147
	v_add_u32_e32 v151, 0, v3
	s_mov_b64 s[14:15], 0x200000
	s_mov_b32 s67, 0x200000
	s_mov_b64 s[16:17], 0x240000
	s_mov_b32 s68, 0x240000
	s_mov_b64 s[18:19], 0x280000
	s_mov_b32 s69, 0x280000
	s_mov_b64 s[20:21], 0x2c0000
	s_mov_b32 s70, 0x2c0000
	s_barrier
	s_branch .LBB0_1329

; #define PG8_STAGE(bufoff, gbase, voff) do { _Pragma("unroll") for (int _i = 0; _i < 2; ++_i) \
;         __builtin_amdgcn_global_load_lds((const unsigned*)((const char*)(gbase) + (voff)[_i]), (PG8_LAS unsigned*)(lds + (bufoff) + ldsw + _i * 8192), 16, 0, 0); } while (0)
; #define PG8_WAIT_V(n) asm volatile("s_waitcnt vmcnt(" #n ")" ::: "memory")
; #define PG8_BAR __builtin_amdgcn_s_barrier()
; template <class Epi, class Sched, bool ALIGN_EPI = false, bool SP2 = false>
; __device__ __forceinline__ void gemm_phase(PG8_LAS unsigned char* lds, const Gemm g, const Sched& S, const Epi& E) {
;     ...
;     if constexpr (SP2) {
;         PG8_STAGE(PG8_SB(0, 0), cB, voffB); PG8_STAGE(PG8_SB(0, 1), cB + hstep, voffB); PG8_STAGE(PG8_SA(0, 0), cA, voffA); PG8_STAGE(PG8_SA(0, 1), cA + hstep, voffA);
;         if (wr == 1) PG8_BAR;
;         PG8_WAIT_V(2); PG8_BAR;
;         PG8_STAGE(PG8_SB(1, 0), cB + kstep, voffB); PG8_STAGE(PG8_SA(1, 0), cA + kstep, voffA); PG8_STAGE(PG8_SB(1, 1), cB + hstep + kstep, voffB);
;         PG8_WAIT_V(6); PG8_BAR;
.LBB0_1402:
	s_lshl_b32 s5, s5, 5
	s_mov_b64 s[8:9], 0x80
	s_and_b32 s5, s5, 0x60
	s_add_i32 m0, s33, 0x18000
	v_lshl_add_u64 v[6:7], v[6:7], 0, s[8:9]
	s_lshl_b32 s14, s11, 13
	s_lshl_b32 s15, s5, 7
	global_load_lds_dwordx4 v[6:7], off
	v_lshl_add_u64 v[4:5], v[4:5], 0, s[8:9]
	s_add_i32 m0, s33, 0x1a000
	s_add_i32 s59, s33, 0x8000
	s_add_i32 s60, s33, 0xa000
	global_load_lds_dwordx4 v[4:5], off
	v_lshl_add_u64 v[0:1], v[0:1], 0, s[8:9]
	s_mov_b32 m0, s59
	s_add_u32 s12, s46, 0x200080
	global_load_lds_dwordx4 v[0:1], off
	v_lshl_add_u64 v[0:1], v[2:3], 0, s[8:9]
	s_mov_b32 m0, s60
	s_addc_u32 s13, s47, 0
	global_load_lds_dwordx4 v[0:1], off
	s_add_i32 m0, s33, 0x1c000
	v_lshl_add_u64 v[0:1], s[12:13], 0, v[170:171]
	global_load_lds_dwordx4 v[0:1], off
	v_lshl_add_u64 v[0:1], s[12:13], 0, v[174:175]
	s_add_i32 m0, s33, 0x1e000
	s_cmpk_lt_u32 s10, 0x100
	global_load_lds_dwordx4 v[0:1], off
	s_cmp_lg_u32 s11, 1
	s_cbranch_scc1 .Lgp_skip_12
	s_barrier
.Lgp_skip_12:
	s_cmpk_lt_u32 s10, 0x100
	s_waitcnt vmcnt(8)
	s_barrier
	v_lshrrev_b32_e32 v1, 1, v8
	v_and_b32_e32 v1, 24, v1
	v_and_b32_e32 v0, 15, v8
	v_lshlrev_b32_e32 v2, 1, v1
	v_lshl_or_b32 v199, s11, 6, v0
	v_lshl_or_b32 v0, v0, 6, v2
	v_lshlrev_b32_e32 v2, 2, v8
	v_and_b32_e32 v2, 32, v2
	v_bitop3_b32 v3, v0, s14, v2 bitop3:0xde
	v_bitop3_b32 v200, v0, s15, v2 bitop3:0xde
	v_lshlrev_b32_e32 v0, 17, v9
	v_and_b32_e32 v0, 0xfffc0000, v0
	v_or_b32_e32 v201, s5, v1
	v_lshl_add_u32 v0, v10, 14, v0
	v_and_b32_e32 v1, 1, v9
	v_lshl_or_b32 v0, v1, 6, v0
	v_lshl_add_u32 v176, v11, 1, v0
	v_lshlrev_b32_e32 v0, 17, v12
	v_and_b32_e32 v0, 0xfffc0000, v0
	s_waitcnt vmcnt(6)
	v_lshl_add_u32 v0, v13, 14, v0
	v_and_b32_e32 v1, 1, v12
	s_cselect_b64 s[10:11], -1, 0
	v_lshl_or_b32 v0, v1, 6, v0
	s_add_i32 s63, 0, 0x10000
	s_add_i32 s64, 0, 0x14000
	s_sext_i32_i8 s24, s4
	s_ashr_i32 s61, s56, 31
	s_mov_b32 s62, s56
	v_mov_b32_e32 v177, v171
	v_lshl_add_u32 v178, v14, 1, v0
	v_mov_b32_e32 v179, v171
	v_mov_b64_e32 v[180:181], 0x100
	v_mov_b64_e32 v[182:183], 0xff
	v_add_u32_e32 v202, s63, v200
	v_add_u32_e32 v203, s64, v200
	v_add_u32_e32 v204, 0, v3
	s_mov_b64 s[12:13], 0x80000
	s_mov_b64 s[14:15], 0x90000
	s_mov_b64 s[16:17], 0xa0000
	s_mov_b64 s[18:19], 0xb0000
	s_barrier
	s_branch .LBB0_1405
